# split the one-time weight conversion between the two batch streams (stream 0 converts FFN2 + PLE gate weights, stream 1 the rest; second ready-flag) so both streams finish closer together
# speedup vs baseline: 1.0404x; 1.0055x over previous
; #define LAS __attribute__((address_space(3)))
; __device__ __forceinline__ int fresh_tid() { int t = threadIdx.x; asm volatile("" : "+v"(t)); return t; }
; #define PIN(i) ((const float*)(const GAS float*)karg_q(i))
; __device__ __forceinline__ void cvt_run(const CvtDesc& d, LAS unsigned char* lds, int wg, int nwg) {
;     const int tid = fresh_tid(), wid = tid >> 6, lane = tid & 63, gw = wg * 8 + wid, NGW = nwg * 8; LAS float* scr = (LAS float*)(lds + wid * 8704);
;     const int nitems = (d.K >> 6) * (d.nslots >> 5);
;     int it = gw; if (it >= nitems) return;
;     f32x4 vN[8]; CvtPos pN = cvt_pos(d, it); cvt_load(d, pN, vN, lane);
; __global__ __launch_bounds__(512, 2) void fwd_megakernel(Params P) {
;     ...
;     if (grp == 1) {
;         { CvtDesc d{PIN(5), nullptr, (bf16_t*)(ws + OFF_W1B), DFF, DM, DM, 0, nullptr}; cvt_run(d, lds, gi, ng); }
;         { CvtDesc d{PIN(8), nullptr, (bf16_t*)(ws + OFF_WQKV), DM, NQKV, NQKV, 2, PIN(7)}; cvt_run(d, lds, gi, ng); }
;         { CvtDesc d{PIN(11), nullptr, (bf16_t*)(ws + OFF_WO), DM, DM, DM, 0, nullptr}; cvt_run(d, lds, gi, ng); }
;         { CvtDesc d{PIN(14), PIN(15), (bf16_t*)(ws + OFF_W2A), DM, DFF, 2 * DFF, 1, PIN(13)}; cvt_run(d, lds, gi, ng); }
;         { CvtDesc d{PIN(16), nullptr, (bf16_t*)(ws + OFF_W2B), DFF, DM, DM, 0, nullptr}; cvt_run(d, lds, gi, ng); }
;         { CvtDesc d{PIN(19), nullptr, (bf16_t*)(ws + OFF_WPG), DM, DM, DM, 0, PIN(18)}; cvt_run(d, lds, gi, ng); }
;         { CvtDesc d{PIN(20), nullptr, (bf16_t*)(ws + OFF_WPP), PLE, DM, DM, 0, nullptr}; cvt_run(d, lds, gi, ng); }
.LBB0_95:
	v_writelane_b32 v232, s60, 4
	s_nop 1
	v_writelane_b32 v232, s61, 5
	s_or_b64 exec, exec, s[4:5]
	s_and_b32 s60, s2, 3
	s_add_u32 s6, s16, 0x1fb5c000
	s_addc_u32 s7, s17, 0
	s_ashr_i32 s74, s2, 1
	s_and_b32 s3, s74, -4
	s_or_b32 s35, s3, s60
	s_ashr_i32 s95, s67, 1
	v_readlane_b32 s3, v232, 0
	s_cmp_lg_u32 s3, 0
	s_waitcnt lgkmcnt(0)
	s_barrier
	s_cbranch_scc1 .Lconv1_entry
	s_lshl_b32 s10, s35, 3
	s_lshl_b32 s3, s95, 3
	s_branch .LBB0_117
.Lconv1_entry:
	v_mov_b32_e32 v1, v158
	s_lshl_b32 s10, s35, 3
	v_ashrrev_i32_e32 v0, 6, v1
	v_add_u32_e32 v74, s10, v0
	s_movk_i32 s11, 0x1600
	s_lshl_b32 s3, s95, 3
	v_cmp_gt_i32_e32 vcc, s11, v74
	s_and_saveexec_b64 s[8:9], vcc
	s_cbranch_execz .LBB0_101
	v_ashrrev_i32_e32 v2, 31, v74
	v_lshrrev_b32_e32 v2, 26, v2
	v_add_u32_e32 v3, v74, v2
	s_load_dwordx2 s[12:13], s[0:1], 0x28
	v_lshlrev_b32_e32 v2, 5, v3
	v_and_b32_e32 v2, 0xfffff800, v2
	v_lshlrev_b32_e32 v4, 5, v74
	v_bfe_u32 v75, v1, 3, 3
	v_and_b32_e32 v70, 0xffffffc0, v3
	v_sub_u32_e32 v66, v4, v2
	v_or_b32_e32 v4, v70, v75
	v_ashrrev_i32_e32 v5, 31, v4
	v_lshlrev_b32_e32 v2, 2, v1
	v_lshlrev_b64 v[4:5], 13, v[4:5]
	v_and_b32_e32 v2, 28, v2
	s_waitcnt lgkmcnt(0)
	v_lshl_add_u64 v[4:5], s[12:13], 0, v[4:5]
	v_ashrrev_i32_e32 v67, 31, v66
	v_mov_b32_e32 v65, 0
	v_lshl_add_u64 v[4:5], v[66:67], 2, v[4:5]
	v_lshlrev_b32_e32 v64, 2, v2
	v_lshl_add_u64 v[4:5], v[4:5], 0, v[64:65]
	s_mov_b32 s4, 0x70000
	v_add_co_u32_e32 v6, vcc, s4, v4
	s_mov_b32 s4, 0x60000
	s_nop 0
	v_addc_co_u32_e32 v7, vcc, 0, v5, vcc
	global_load_dwordx4 v[16:19], v[6:7], off
	v_add_co_u32_e32 v6, vcc, s4, v4
	s_mov_b32 s4, 0x50000
	s_nop 0
	v_addc_co_u32_e32 v7, vcc, 0, v5, vcc
	v_add_co_u32_e32 v8, vcc, s4, v4
	s_mov_b32 s4, 0x40000
	s_nop 0
	v_addc_co_u32_e32 v9, vcc, 0, v5, vcc
	global_load_dwordx4 v[28:31], v[6:7], off
	global_load_dwordx4 v[40:43], v[8:9], off
	v_add_co_u32_e32 v6, vcc, s4, v4
	s_mov_b32 s4, 0x30000
	s_nop 0
	v_addc_co_u32_e32 v7, vcc, 0, v5, vcc
	v_add_co_u32_e32 v8, vcc, s4, v4
	s_mov_b32 s4, 0x20000
	s_nop 0
	v_addc_co_u32_e32 v9, vcc, 0, v5, vcc
	global_load_dwordx4 v[44:47], v[6:7], off
	global_load_dwordx4 v[48:51], v[8:9], off
	v_add_co_u32_e32 v6, vcc, s4, v4
	s_mov_b32 s4, 0x10000
	s_nop 0
	v_addc_co_u32_e32 v7, vcc, 0, v5, vcc
	v_add_co_u32_e32 v8, vcc, s4, v4
	s_add_u32 s14, s16, 0x2c00000
	s_nop 0
	v_addc_co_u32_e32 v9, vcc, 0, v5, vcc
	global_load_dwordx4 v[52:55], v[6:7], off
	global_load_dwordx4 v[56:59], v[8:9], off
	global_load_dwordx4 v[60:63], v[4:5], off
	s_movk_i32 s4, 0x2200
	s_addc_u32 s15, s17, 0
	v_mul_lo_u32 v3, v0, s4
	s_lshl_b32 s4, s74, 3
	s_lshl_b32 s5, s60, 3
	v_add_u32_e32 v3, 0, v3
	v_and_b32_e32 v1, 7, v1
	s_and_b32 s4, s4, 0x7ffffe0
	s_add_i32 s5, s5, s3
	v_lshl_add_u32 v5, v1, 4, v3
	v_mul_u32_u24_e32 v6, 0x84, v75
	v_lshlrev_b32_e32 v4, 3, v1
	v_mul_u32_u24_e32 v1, 0x420, v1
	v_lshlrev_b32_e32 v7, 2, v75
	s_add_i32 s5, s5, s4
	v_add3_u32 v78, v3, v1, v7
	v_add_lshl_u32 v79, s5, v0, 5
	v_lshlrev_b32_e32 v68, 2, v2
	v_add_u32_e32 v80, v5, v6
	v_lshlrev_b32_e32 v64, 1, v4
	v_or_b32_e32 v67, 8, v75
	v_or_b32_e32 v76, 16, v75
	v_or_b32_e32 v77, 24, v75
	s_lshl_b32 s24, s95, 8
	s_mov_b64 s[20:21], 0
	s_movk_i32 s25, 0x15ff
	s_movk_i32 s26, 0x2c00
	s_waitcnt vmcnt(7)
	v_mov_b64_e32 v[38:39], v[18:19]
	v_mov_b64_e32 v[36:37], v[16:17]
	s_waitcnt vmcnt(6)
	v_mov_b64_e32 v[34:35], v[30:31]
	s_waitcnt vmcnt(5)
	v_mov_b64_e32 v[24:25], v[40:41]
	v_mov_b64_e32 v[32:33], v[28:29]
	v_mov_b64_e32 v[26:27], v[42:43]
	s_waitcnt vmcnt(4)
	v_mov_b64_e32 v[20:21], v[44:45]
	s_waitcnt vmcnt(3)
	v_mov_b64_e32 v[12:13], v[48:49]
	v_mov_b64_e32 v[22:23], v[46:47]
	v_mov_b64_e32 v[14:15], v[50:51]
	s_waitcnt vmcnt(2)
	v_mov_b64_e32 v[8:9], v[52:53]
	s_waitcnt vmcnt(1)
	v_mov_b64_e32 v[4:5], v[56:57]
	s_waitcnt vmcnt(0)
	v_mov_b64_e32 v[0:1], v[60:61]
	v_mov_b64_e32 v[10:11], v[54:55]
	v_mov_b64_e32 v[6:7], v[58:59]
	v_mov_b64_e32 v[2:3], v[62:63]
	s_branch .LBB0_99

; #define LAS __attribute__((address_space(3)))
; __device__ __forceinline__ int fresh_tid() { int t = threadIdx.x; asm volatile("" : "+v"(t)); return t; }
; #define PIN(i) ((const float*)(const GAS float*)karg_q(i))
; __device__ __forceinline__ void cvt_run(const CvtDesc& d, LAS unsigned char* lds, int wg, int nwg) {
;     const int tid = fresh_tid(), wid = tid >> 6, lane = tid & 63, gw = wg * 8 + wid, NGW = nwg * 8; LAS float* scr = (LAS float*)(lds + wid * 8704);
;     const int nitems = (d.K >> 6) * (d.nslots >> 5);
;     int it = gw; if (it >= nitems) return;
;     f32x4 vN[8]; CvtPos pN = cvt_pos(d, it); cvt_load(d, pN, vN, lane);
; __global__ __launch_bounds__(512, 2) void fwd_megakernel(Params P) {
;     ...
;         { CvtDesc d{PIN(14), PIN(15), (bf16_t*)(ws + OFF_W2A), DM, DFF, 2 * DFF, 1, PIN(13)}; cvt_run(d, lds, gi, ng); }
;         { CvtDesc d{PIN(16), nullptr, (bf16_t*)(ws + OFF_W2B), DFF, DM, DM, 0, nullptr}; cvt_run(d, lds, gi, ng); }
;         { CvtDesc d{PIN(19), nullptr, (bf16_t*)(ws + OFF_WPG), DM, DM, DM, 0, PIN(18)}; cvt_run(d, lds, gi, ng); }
.LBB0_117:
	s_or_b64 exec, exec, s[8:9]
	v_readlane_b32 s98, v232, 0
	s_cmp_lg_u32 s98, 0
	s_cbranch_scc1 .LBB0_136
	v_mov_b32_e32 v0, v158
	s_movk_i32 s11, 0x2c00
	v_ashrrev_i32_e32 v1, 6, v0
	v_add_u32_e32 v67, s10, v1
	v_cmp_gt_i32_e32 vcc, s11, v67
	s_and_saveexec_b64 s[8:9], vcc
	s_cbranch_execz .LBB0_124
	s_load_dwordx4 s[12:15], s[0:1], 0x68
	s_load_dwordx2 s[20:21], s[0:1], 0x78
	s_mov_b32 s30, 0x2e8ba2e9
	v_mul_hi_i32 v2, v67, s30
	v_lshrrev_b32_e32 v3, 31, v2
	v_ashrrev_i32_e32 v2, 6, v2
	v_add_u32_e32 v5, v2, v3
	s_movk_i32 s4, 0xfea0
	v_mad_i32_i24 v4, v5, s4, v67
	v_and_b32_e32 v2, 0x100, v0
	v_lshlrev_b32_e32 v71, 5, v4
	s_waitcnt lgkmcnt(0)
	v_mov_b32_e32 v3, s21
	v_mov_b32_e32 v7, s15
	v_cmp_eq_u32_e32 vcc, 0, v2
	v_and_b32_e32 v6, 0x60, v71
	v_mov_b32_e32 v2, s20
	v_cndmask_b32_e32 v3, v3, v7, vcc
	v_mov_b32_e32 v7, s14
	v_lshlrev_b32_e32 v4, 4, v4
	s_movk_i32 s31, 0xff80
	v_bfe_u32 v70, v0, 3, 3
	v_lshlrev_b32_e32 v68, 6, v5
	v_cndmask_b32_e32 v2, v2, v7, vcc
	v_and_or_b32 v4, v4, s31, v6
	v_lshlrev_b32_e32 v6, 2, v0
	v_or_b32_e32 v5, v68, v70
	s_movk_i32 s33, 0x5800
	v_and_b32_e32 v6, 28, v6
	v_mad_i64_i32 v[2:3], s[4:5], v5, s33, v[2:3]
	v_ashrrev_i32_e32 v5, 31, v4
	v_mov_b32_e32 v65, 0
	v_lshl_add_u64 v[2:3], v[4:5], 2, v[2:3]
	v_lshlrev_b32_e32 v64, 2, v6
	v_lshl_add_u64 v[2:3], v[2:3], 0, v[64:65]
	s_mov_b32 s4, 0x134000
	v_add_co_u32_e32 v4, vcc, s4, v2
	s_mov_b32 s4, 0x108000
	s_nop 0
	v_addc_co_u32_e32 v5, vcc, 0, v3, vcc
	global_load_dwordx4 v[24:27], v[4:5], off
	v_add_co_u32_e32 v4, vcc, s4, v2
	s_mov_b32 s4, 0xdc000
	s_nop 0
	v_addc_co_u32_e32 v5, vcc, 0, v3, vcc
	v_add_co_u32_e32 v8, vcc, s4, v2
	s_mov_b32 s4, 0xb0000
	s_nop 0
	v_addc_co_u32_e32 v9, vcc, 0, v3, vcc
	global_load_dwordx4 v[36:39], v[4:5], off
	global_load_dwordx4 v[40:43], v[8:9], off
	v_add_co_u32_e32 v4, vcc, s4, v2
	s_mov_b32 s4, 0x84000
	s_nop 0
	v_addc_co_u32_e32 v5, vcc, 0, v3, vcc
	v_add_co_u32_e32 v8, vcc, s4, v2
	s_mov_b32 s4, 0x58000
	s_nop 0
	v_addc_co_u32_e32 v9, vcc, 0, v3, vcc
	global_load_dwordx4 v[44:47], v[4:5], off
	global_load_dwordx4 v[48:51], v[8:9], off
	v_add_co_u32_e32 v4, vcc, s4, v2
	s_mov_b32 s4, 0x2c000
	s_nop 0
	v_addc_co_u32_e32 v5, vcc, 0, v3, vcc
	v_add_co_u32_e32 v8, vcc, s4, v2
	s_movk_i32 s4, 0x2200
	s_nop 0
	v_addc_co_u32_e32 v9, vcc, 0, v3, vcc
	global_load_dwordx4 v[52:55], v[4:5], off
	global_load_dwordx4 v[56:59], v[8:9], off
	global_load_dwordx4 v[60:63], v[2:3], off
	v_mul_lo_u32 v1, v1, s4
	s_add_u32 s22, s16, 0x4200000
	v_add_u32_e32 v1, 0, v1
	v_and_b32_e32 v2, 7, v0
	s_addc_u32 s23, s17, 0
	v_lshl_add_u32 v3, v2, 4, v1
	v_mul_u32_u24_e32 v4, 0x84, v70
	v_lshlrev_b32_e32 v0, 3, v2
	v_mul_u32_u24_e32 v2, 0x420, v2
	v_lshlrev_b32_e32 v5, 2, v70
	v_add3_u32 v75, v1, v2, v5
	s_cmp_lg_u64 s[12:13], 0
	v_lshlrev_b32_e32 v66, 2, v6
	v_add_u32_e32 v76, v3, v4
	v_lshlrev_b32_e32 v64, 1, v0
	v_or_b32_e32 v72, 8, v70
	v_or_b32_e32 v73, 16, v70
	v_or_b32_e32 v74, 24, v70
	s_mov_b64 s[24:25], 0
	s_cselect_b64 s[26:27], -1, 0
	s_movk_i32 s34, 0x2bff
	v_mov_b32_e32 v77, v71
	s_waitcnt vmcnt(7)
	v_mov_b64_e32 v[34:35], v[26:27]
	v_mov_b64_e32 v[32:33], v[24:25]
	s_waitcnt vmcnt(6)
	v_mov_b64_e32 v[28:29], v[36:37]
	s_waitcnt vmcnt(5)
	v_mov_b64_e32 v[20:21], v[40:41]
	v_mov_b64_e32 v[30:31], v[38:39]
	v_mov_b64_e32 v[22:23], v[42:43]
	s_waitcnt vmcnt(4)
	v_mov_b64_e32 v[16:17], v[44:45]
	s_waitcnt vmcnt(3)
	v_mov_b64_e32 v[12:13], v[48:49]
	v_mov_b64_e32 v[18:19], v[46:47]
	v_mov_b64_e32 v[14:15], v[50:51]
	s_waitcnt vmcnt(2)
	v_mov_b64_e32 v[8:9], v[52:53]
	s_waitcnt vmcnt(1)
	v_mov_b64_e32 v[4:5], v[56:57]
	s_waitcnt vmcnt(0)
	v_mov_b64_e32 v[0:1], v[60:61]
	v_mov_b64_e32 v[10:11], v[54:55]
	v_mov_b64_e32 v[6:7], v[58:59]
	v_mov_b64_e32 v[2:3], v[62:63]
	s_branch .LBB0_120

; #define LAS __attribute__((address_space(3)))
; __device__ __forceinline__ int fresh_tid() { int t = threadIdx.x; asm volatile("" : "+v"(t)); return t; }
; #define PIN(i) ((const float*)(const GAS float*)karg_q(i))
; __device__ __forceinline__ void cvt_run(const CvtDesc& d, LAS unsigned char* lds, int wg, int nwg) {
;     const int tid = fresh_tid(), wid = tid >> 6, lane = tid & 63, gw = wg * 8 + wid, NGW = nwg * 8; LAS float* scr = (LAS float*)(lds + wid * 8704);
;     const int nitems = (d.K >> 6) * (d.nslots >> 5);
;     int it = gw; if (it >= nitems) return;
;     f32x4 vN[8]; CvtPos pN = cvt_pos(d, it); cvt_load(d, pN, vN, lane);
; __global__ __launch_bounds__(512, 2) void fwd_megakernel(Params P) {
;     ...
;         { CvtDesc d{PIN(19), nullptr, (bf16_t*)(ws + OFF_WPG), DM, DM, DM, 0, PIN(18)}; cvt_run(d, lds, gi, ng); }
;         { CvtDesc d{PIN(20), nullptr, (bf16_t*)(ws + OFF_WPP), PLE, DM, DM, 0, nullptr}; cvt_run(d, lds, gi, ng); }
.LBB0_136:
	s_or_b64 exec, exec, s[8:9]
	v_readlane_b32 s98, v232, 0
	s_cmp_lg_u32 s98, 0
	s_cbranch_scc0 .LBB0_141
	v_mov_b32_e32 v1, v158
	s_nop 0
	v_ashrrev_i32_e32 v0, 6, v1
	v_add_u32_e32 v74, s10, v0
	s_movk_i32 s10, 0x100
	v_cmp_gt_i32_e32 vcc, s10, v74
	s_and_saveexec_b64 s[8:9], vcc
	s_cbranch_execz .LBB0_141
	v_ashrrev_i32_e32 v2, 31, v74
	v_lshrrev_b32_e32 v2, 26, v2
	v_add_u32_e32 v3, v74, v2
	s_load_dwordx2 s[12:13], s[0:1], 0xa0
	v_lshlrev_b32_e32 v2, 5, v3
	v_and_b32_e32 v2, 0xfffff800, v2
	v_lshlrev_b32_e32 v4, 5, v74
	v_bfe_u32 v75, v1, 3, 3
	v_and_b32_e32 v70, 0xffffffc0, v3
	v_sub_u32_e32 v66, v4, v2
	v_or_b32_e32 v4, v70, v75
	v_ashrrev_i32_e32 v5, 31, v4
	v_lshlrev_b32_e32 v2, 2, v1
	v_lshlrev_b64 v[4:5], 13, v[4:5]
	v_and_b32_e32 v2, 28, v2
	s_waitcnt lgkmcnt(0)
	v_lshl_add_u64 v[4:5], s[12:13], 0, v[4:5]
	v_ashrrev_i32_e32 v67, 31, v66
	v_mov_b32_e32 v65, 0
	v_lshl_add_u64 v[4:5], v[66:67], 2, v[4:5]
	v_lshlrev_b32_e32 v64, 2, v2
	v_lshl_add_u64 v[4:5], v[4:5], 0, v[64:65]
	s_mov_b32 s4, 0x70000
	v_add_co_u32_e32 v6, vcc, s4, v4
	s_mov_b32 s4, 0x60000
	s_nop 0
	v_addc_co_u32_e32 v7, vcc, 0, v5, vcc
	global_load_dwordx4 v[16:19], v[6:7], off
	v_add_co_u32_e32 v6, vcc, s4, v4
	s_mov_b32 s4, 0x50000
	s_nop 0
	v_addc_co_u32_e32 v7, vcc, 0, v5, vcc
	v_add_co_u32_e32 v8, vcc, s4, v4
	s_mov_b32 s4, 0x40000
	s_nop 0
	v_addc_co_u32_e32 v9, vcc, 0, v5, vcc
	global_load_dwordx4 v[28:31], v[6:7], off
	global_load_dwordx4 v[40:43], v[8:9], off
	v_add_co_u32_e32 v6, vcc, s4, v4
	s_mov_b32 s4, 0x30000
	s_nop 0
	v_addc_co_u32_e32 v7, vcc, 0, v5, vcc
	v_add_co_u32_e32 v8, vcc, s4, v4
	s_mov_b32 s4, 0x20000
	s_nop 0
	v_addc_co_u32_e32 v9, vcc, 0, v5, vcc
	global_load_dwordx4 v[44:47], v[6:7], off
	global_load_dwordx4 v[48:51], v[8:9], off
	v_add_co_u32_e32 v6, vcc, s4, v4
	s_mov_b32 s4, 0x10000
	s_nop 0
	v_addc_co_u32_e32 v7, vcc, 0, v5, vcc
	v_add_co_u32_e32 v8, vcc, s4, v4
	s_add_u32 s14, s16, 0xac00000
	s_nop 0
	v_addc_co_u32_e32 v9, vcc, 0, v5, vcc
	global_load_dwordx4 v[52:55], v[6:7], off
	global_load_dwordx4 v[56:59], v[8:9], off
	global_load_dwordx4 v[60:63], v[4:5], off
	s_movk_i32 s4, 0x2200
	s_addc_u32 s15, s17, 0
	v_mul_lo_u32 v3, v0, s4
	s_lshl_b32 s4, s74, 3
	s_lshl_b32 s5, s60, 3
	v_and_b32_e32 v1, 7, v1
	v_add_u32_e32 v3, 0, v3
	s_and_b32 s4, s4, 0x7ffffe0
	s_add_i32 s5, s5, s3
	v_mul_u32_u24_e32 v5, 0x84, v75
	v_lshlrev_b32_e32 v4, 3, v1
	v_mul_u32_u24_e32 v6, 0x420, v1
	v_lshlrev_b32_e32 v7, 2, v75
	v_lshl_add_u32 v1, v1, 4, v3
	s_add_i32 s5, s5, s4
	v_lshlrev_b32_e32 v68, 2, v2
	v_add3_u32 v78, v3, v6, v7
	v_add_lshl_u32 v79, s5, v0, 5
	v_add_u32_e32 v80, v1, v5
	v_lshlrev_b32_e32 v64, 1, v4
	s_mov_b64 s[20:21], 0
	s_movk_i32 s11, 0xff
	v_or_b32_e32 v67, 8, v75
	v_or_b32_e32 v76, 16, v75
	v_or_b32_e32 v77, 24, v75
	s_lshl_b32 s24, s95, 8
	s_waitcnt vmcnt(7)
	v_mov_b64_e32 v[38:39], v[18:19]
	v_mov_b64_e32 v[36:37], v[16:17]
	s_waitcnt vmcnt(6)
	v_mov_b64_e32 v[34:35], v[30:31]
	s_waitcnt vmcnt(5)
	v_mov_b64_e32 v[24:25], v[40:41]
	v_mov_b64_e32 v[32:33], v[28:29]
	v_mov_b64_e32 v[26:27], v[42:43]
	s_waitcnt vmcnt(4)
	v_mov_b64_e32 v[20:21], v[44:45]
	s_waitcnt vmcnt(3)
	v_mov_b64_e32 v[12:13], v[48:49]
	v_mov_b64_e32 v[22:23], v[46:47]
	v_mov_b64_e32 v[14:15], v[50:51]
	s_waitcnt vmcnt(2)
	v_mov_b64_e32 v[8:9], v[52:53]
	s_waitcnt vmcnt(1)
	v_mov_b64_e32 v[4:5], v[56:57]
	s_waitcnt vmcnt(0)
	v_mov_b64_e32 v[0:1], v[60:61]
	v_mov_b64_e32 v[10:11], v[54:55]
	v_mov_b64_e32 v[6:7], v[58:59]
	v_mov_b64_e32 v[2:3], v[62:63]
	s_branch .LBB0_139

; __global__ __launch_bounds__(512, 2) void fwd_megakernel(Params P) {
;     ...
;         xcd_barrier(xg);
;         if (gi == 0 && threadIdx.x == 0) __hip_atomic_store(wflag, 1u, __ATOMIC_RELAXED, __HIP_MEMORY_SCOPE_AGENT);
.LBB0_193:
	s_or_b64 exec, exec, s[4:5]
	s_waitcnt lgkmcnt(0)
	v_or_b32_e32 v0, s35, v158
	v_cmp_eq_u32_e32 vcc, 0, v0
	s_barrier
	s_and_saveexec_b64 s[4:5], vcc
	s_cbranch_execz .LBB0_195
	v_readlane_b32 s98, v232, 0
	s_cmp_eq_u32 s98, 0
	s_cselect_b32 s98, 0x80, 0
	v_mov_b32_e32 v0, s98
	v_mov_b32_e32 v1, 1
	global_store_dword v0, v1, s[6:7] sc1

; #define PIN(i) ((const float*)(const GAS float*)karg_q(i))
; __global__ __launch_bounds__(512, 2) void fwd_megakernel(Params P) {
;     ...
;         if (threadIdx.x == 0) { unsigned sp = 0; while (__hip_atomic_load(wflag, __ATOMIC_RELAXED, __HIP_MEMORY_SCOPE_AGENT) == 0u && ++sp < (1u << 24)) __builtin_amdgcn_s_sleep(8); }
;     }
;     ...
;     rowwise_phase<3>(nullptr, HB, F, PIN(12), 1.0f, RS, nullptr, ci, nc, crow0, crow0 + CR);
;     xcd_barrier(xc);
.LBB0_737:
	s_or_b64 exec, exec, s[8:9]
	v_readlane_b32 s98, v232, 0
	s_cmp_eq_u32 s98, 0
	s_cbranch_scc1 .Lw0_done
	v_cmp_eq_u32_e32 vcc, 0, v158
	s_and_saveexec_b64 s[100:101], vcc
	s_cbranch_execz .Lw0_join
	s_add_u32 s98, s16, 0x1fb5c000
	s_addc_u32 s99, s17, 0
	v_mov_b32_e32 v233, 0x80
	v_mov_b32_e32 v234, 0
.Lw0_spin:
	global_load_dword v235, v233, s[98:99] sc1
	s_waitcnt vmcnt(0)
	v_cmp_ne_u32_e32 vcc, 0, v235
	s_cbranch_vccnz .Lw0_join
	s_sleep 8
	v_add_u32_e32 v234, 1, v234
	v_cmp_gt_u32_e32 vcc, 0x1000000, v234
	s_cbranch_vccnz .Lw0_spin
.Lw0_join:
	s_or_b64 exec, exec, s[100:101]
.Lw0_done:
	s_waitcnt vmcnt(0)
	s_barrier
	s_and_saveexec_b64 s[2:3], s[74:75]
	s_cbranch_execz .LBB0_789
	s_add_i32 s6, 0, 0x21110
	v_mov_b32_e32 v0, s6
	s_waitcnt vmcnt(0) expcnt(0) lgkmcnt(0)
	ds_read_b32 v2, v0
	s_add_i32 s6, 0, 0x21114
	v_mov_b32_e32 v0, s6
	ds_read_b32 v0, v0
	s_waitcnt lgkmcnt(1)
	v_cmp_ne_u32_e32 vcc, 0, v2
	s_cbranch_vccnz .LBB0_753
	s_add_u32 s6, s18, 0x1000
	s_addc_u32 s7, s19, 0
	s_add_u32 s8, s18, 0x1100
	s_addc_u32 s9, s19, 0
	s_add_u32 s30, s18, 0x1200
	s_addc_u32 s31, s19, 0
	s_add_u32 s34, s18, 0x1300
	s_addc_u32 s35, s19, 0
	s_mov_b32 s10, 1
	v_mov_b32_e32 v16, 0
	s_branch .LBB0_741

; __global__ __launch_bounds__(512, 2) void fwd_megakernel(Params P) {
	.amdhsa_kernel _Z14fwd_megakernel6Params
		.amdhsa_group_segment_fixed_size 0
		.amdhsa_private_segment_fixed_size 0
		.amdhsa_kernarg_size 448
		.amdhsa_user_sgpr_count 2
		.amdhsa_user_sgpr_dispatch_ptr 0
		.amdhsa_user_sgpr_queue_ptr 0
		.amdhsa_user_sgpr_kernarg_segment_ptr 1
		.amdhsa_user_sgpr_dispatch_id 0
		.amdhsa_user_sgpr_kernarg_preload_length 0
		.amdhsa_user_sgpr_kernarg_preload_offset 0
		.amdhsa_user_sgpr_private_segment_size 0
		.amdhsa_uses_dynamic_stack 0
		.amdhsa_enable_private_segment 0
		.amdhsa_system_sgpr_workgroup_id_x 1
		.amdhsa_system_sgpr_workgroup_id_y 0
		.amdhsa_system_sgpr_workgroup_id_z 0
		.amdhsa_system_sgpr_workgroup_info 0
		.amdhsa_system_vgpr_workitem_id 2
		.amdhsa_next_free_vgpr 240
		.amdhsa_next_free_sgpr 102
		.amdhsa_accum_offset 240
		.amdhsa_reserve_vcc 1
		.amdhsa_float_round_mode_32 0
		.amdhsa_float_round_mode_16_64 0
		.amdhsa_float_denorm_mode_32 3
		.amdhsa_float_denorm_mode_16_64 3
		.amdhsa_dx10_clamp 1
		.amdhsa_ieee_mode 1
		.amdhsa_fp16_overflow 0
		.amdhsa_tg_split 0
		.amdhsa_exception_fp_ieee_invalid_op 0
		.amdhsa_exception_fp_denorm_src 0
		.amdhsa_exception_fp_ieee_div_zero 0
		.amdhsa_exception_fp_ieee_overflow 0
		.amdhsa_exception_fp_ieee_underflow 0
		.amdhsa_exception_fp_ieee_inexact 0
		.amdhsa_exception_int_div_zero 0
	.end_amdhsa_kernel

; __global__ __launch_bounds__(512, 2) void fwd_megakernel(Params P) {
amdhsa.kernels:
  - .agpr_count:     0
    .args:
      - .offset:         0
        .size:           192
        .value_kind:     by_value
      - .offset:         192
        .size:           4
        .value_kind:     hidden_block_count_x
      - .offset:         196
        .size:           4
        .value_kind:     hidden_block_count_y
      - .offset:         200
        .size:           4
        .value_kind:     hidden_block_count_z
      - .offset:         204
        .size:           2
        .value_kind:     hidden_group_size_x
      - .offset:         206
        .size:           2
        .value_kind:     hidden_group_size_y
      - .offset:         208
        .size:           2
        .value_kind:     hidden_group_size_z
      - .offset:         210
        .size:           2
        .value_kind:     hidden_remainder_x
      - .offset:         212
        .size:           2
        .value_kind:     hidden_remainder_y
      - .offset:         214
        .size:           2
        .value_kind:     hidden_remainder_z
      - .offset:         232
        .size:           8
        .value_kind:     hidden_global_offset_x
      - .offset:         240
        .size:           8
        .value_kind:     hidden_global_offset_y
      - .offset:         248
        .size:           8
        .value_kind:     hidden_global_offset_z
      - .offset:         256
        .size:           2
        .value_kind:     hidden_grid_dims
      - .offset:         280
        .size:           8
        .value_kind:     hidden_multigrid_sync_arg
      - .offset:         312
        .size:           4
        .value_kind:     hidden_dynamic_lds_size
    .group_segment_fixed_size: 0
    .kernarg_segment_align: 8
    .kernarg_segment_size: 448
    .language:       OpenCL C
    .language_version:
      - 2
      - 0
    .max_flat_workgroup_size: 512
    .name:           _Z14fwd_megakernel6Params
    .private_segment_fixed_size: 0
    .sgpr_count:     108
    .sgpr_spill_count: 29
    .symbol:         _Z14fwd_megakernel6Params.kd
    .uniform_work_group_size: 1
    .uses_dynamic_stack: false
    .vgpr_count:     240
    .vgpr_spill_count: 0
    .wavefront_size: 64
